# attention main loop: the step's two LDS-DMA tile loads issued right behind its first MFMA instead of after the Q.K^T phase (a quarter tile more latency cover in front of the same vmcnt(2) wait); on to
# baseline (speedup 1.0000x reference)
.LBB0_1547:
	v_add_u32_e32 v0, s8, v221
	ds_read_b64_tr_b16 v[192:193], v0 offset:24576
	ds_read_b64_tr_b16 v[194:195], v0 offset:25088
	s_waitcnt lgkmcnt(9)
	v_mfma_f32_32x32x16_bf16 v[112:127], v[188:191], v[148:151], v[48:63]
	v_lshl_add_u64 v[228:229], v[202:203], 0, s[26:27]
	s_add_i32 s8, s40, s46
	s_mov_b32 s9, m0
	s_mov_b32 m0, s8
	s_nop 0
	global_load_lds_dwordx4 v[228:229], off
	s_mov_b32 m0, s9
	v_lshl_add_u64 v[228:229], v[200:201], 0, s[26:27]
	s_add_i32 s8, s38, s47
	s_mov_b32 s9, m0
	s_mov_b32 m0, s8
	s_nop 0
	global_load_lds_dwordx4 v[228:229], off
	s_mov_b32 m0, s9
	v_add_f32_e32 v2, v80, v81
	v_add_f32_e32 v2, v82, v2
	v_add_f32_e32 v2, v83, v2
	v_add_f32_e32 v2, v84, v2
	v_add_f32_e32 v2, v85, v2
	v_cvt_pk_bf16_f32 v156, v80, v81
	v_cvt_pk_bf16_f32 v157, v82, v83
	ds_read_b64_tr_b16 v[188:189], v0 offset:28672
	ds_read_b64_tr_b16 v[190:191], v0 offset:29184
	s_waitcnt lgkmcnt(10)
	v_mfma_f32_32x32x16_bf16 v[96:111], v[184:187], v[148:151], v[48:63]
	v_add_f32_e32 v2, v86, v2
	v_add_f32_e32 v2, v87, v2
	v_add_f32_e32 v2, v88, v2
	v_add_f32_e32 v2, v89, v2
	v_cvt_pk_bf16_f32 v158, v84, v85
	v_cvt_pk_bf16_f32 v159, v86, v87
	ds_read_b64_tr_b16 v[184:185], v0 offset:25600
	ds_read_b64_tr_b16 v[186:187], v0 offset:26112
	s_waitcnt lgkmcnt(11)
	v_mfma_f32_32x32x16_bf16 v[112:127], v[180:183], v[140:143], v[112:127]
	v_add_f32_e32 v2, v90, v2
	v_add_f32_e32 v2, v91, v2
	v_add_f32_e32 v2, v92, v2
	v_add_f32_e32 v2, v93, v2
	v_cvt_pk_bf16_f32 v152, v88, v89
	v_cvt_pk_bf16_f32 v153, v90, v91
	ds_read_b64_tr_b16 v[84:85], v0 offset:29696
	ds_read_b64_tr_b16 v[86:87], v0 offset:30208
	s_waitcnt lgkmcnt(12)
	v_mfma_f32_32x32x16_bf16 v[96:111], v[176:179], v[140:143], v[96:111]
	v_add_f32_e32 v2, v94, v2
	v_add_f32_e32 v2, v95, v2
	v_add_f32_e32 v2, v64, v2
	v_add_f32_e32 v2, v65, v2
	v_cvt_pk_bf16_f32 v154, v92, v93
	v_cvt_pk_bf16_f32 v155, v94, v95
	ds_read_b64_tr_b16 v[80:81], v0 offset:26624
	ds_read_b64_tr_b16 v[82:83], v0 offset:27136
	s_waitcnt lgkmcnt(13)
	v_mfma_f32_32x32x16_bf16 v[112:127], v[172:175], v[132:135], v[112:127]
	v_add_f32_e32 v2, v66, v2
	v_add_f32_e32 v2, v67, v2
	v_add_f32_e32 v2, v68, v2
	v_add_f32_e32 v2, v69, v2
	v_cvt_pk_bf16_f32 v144, v64, v65
	v_cvt_pk_bf16_f32 v145, v66, v67
	ds_read_b64_tr_b16 v[10:11], v0 offset:30720
	ds_read_b64_tr_b16 v[12:13], v0 offset:31232
	s_waitcnt lgkmcnt(14)
	v_mfma_f32_32x32x16_bf16 v[96:111], v[168:171], v[132:135], v[96:111]
	v_add_f32_e32 v2, v70, v2
	v_add_f32_e32 v2, v71, v2
	v_add_f32_e32 v2, v72, v2
	v_add_f32_e32 v2, v73, v2
	v_cvt_pk_bf16_f32 v146, v68, v69
	v_cvt_pk_bf16_f32 v147, v70, v71
	ds_read_b64_tr_b16 v[6:7], v0 offset:27648
	ds_read_b64_tr_b16 v[8:9], v0 offset:28160
	s_waitcnt lgkmcnt(14)
	v_mfma_f32_32x32x16_bf16 v[112:127], v[164:167], v[128:131], v[112:127]
	v_add_f32_e32 v2, v74, v2
	v_add_f32_e32 v2, v75, v2
	v_add_f32_e32 v2, v76, v2
	v_add_f32_e32 v14, v77, v2
	v_cvt_pk_bf16_f32 v136, v72, v73
	v_cvt_pk_bf16_f32 v137, v74, v75
	ds_read_b64_tr_b16 v[2:3], v0 offset:31744
	ds_read_b64_tr_b16 v[4:5], v0 offset:32256
	v_mfma_f32_32x32x16_bf16 v[96:111], v[160:163], v[128:131], v[96:111]
	v_add_f32_e32 v0, v78, v14
	v_add_f32_e32 v0, v79, v0
	v_cvt_pk_bf16_f32 v138, v76, v77
	v_cvt_pk_bf16_f32 v139, v78, v79
	v_max3_f32 v14, v112, v113, v114
	v_max3_f32 v15, v115, v116, v117
	v_max3_f32 v14, v14, v118, v119
	v_max3_f32 v15, v15, v120, v121
	v_max3_f32 v14, v14, v122, v123
	v_max3_f32 v15, v15, v124, v125
	v_max3_f32 v14, v14, v126, v127
	v_max3_f32 v15, v15, v96, v97
	v_max3_f32 v14, v14, v98, v99
	v_max3_f32 v15, v15, v100, v101
	v_max3_f32 v14, v14, v102, v103
	v_max3_f32 v15, v15, v104, v105
	v_max3_f32 v14, v14, v106, v107
	v_max3_f32 v15, v15, v108, v109
	v_max3_f32 v64, v14, v110, v111
	v_add_f32_e32 v14, v223, v0
	v_max_f32_e32 v0, v64, v15
	v_mov_b32_e32 v15, v0
	s_nop 1
	v_permlane32_swap_b32_e32 v0, v15
	v_max_f32_e32 v0, v0, v15
	v_cmp_lt_f32_e32 vcc, s53, v0
	s_cmp_lg_u64 vcc, 0
	s_cselect_b64 s[8:9], -1, 0
	s_cbranch_vccnz .LBB0_1555

.LBB0_1550:
	s_add_i32 s8, s38, 0x2000
	s_cmpk_lg_i32 s38, 0x4000
	s_cselect_b32 s13, s8, 0
	v_add_u32_e32 v4, s40, v221
	ds_read_b64_tr_b16 v[168:169], v4 offset:24576
	ds_read_b64_tr_b16 v[170:171], v4 offset:25088
	s_waitcnt lgkmcnt(9)
	v_mfma_f32_32x32x16_bf16 v[80:95], v[64:67], v[148:151], v[48:63]
	s_add_i32 s8, s38, s46
	s_mov_b32 s9, m0
	s_mov_b32 m0, s8
	s_nop 0
	global_load_lds_dwordx4 v[202:203], off
	s_mov_b32 m0, s9
	s_add_i32 s8, s13, s47
	s_mov_b32 s9, m0
	s_mov_b32 m0, s8
	s_nop 0
	global_load_lds_dwordx4 v[200:201], off
	s_mov_b32 m0, s9
	v_add_f32_e32 v2, v112, v113
	v_add_f32_e32 v2, v114, v2
	v_add_f32_e32 v2, v115, v2
	v_add_f32_e32 v2, v116, v2
	v_add_f32_e32 v2, v117, v2
	v_cvt_pk_bf16_f32 v156, v112, v113
	v_cvt_pk_bf16_f32 v157, v114, v115
	ds_read_b64_tr_b16 v[164:165], v4 offset:28672
	ds_read_b64_tr_b16 v[166:167], v4 offset:29184
	s_waitcnt lgkmcnt(10)
	v_mfma_f32_32x32x16_bf16 v[64:79], v[160:163], v[148:151], v[48:63]
	v_add_f32_e32 v2, v118, v2
	v_add_f32_e32 v2, v119, v2
	v_add_f32_e32 v2, v120, v2
	v_add_f32_e32 v2, v121, v2
	v_cvt_pk_bf16_f32 v158, v116, v117
	v_cvt_pk_bf16_f32 v159, v118, v119
	ds_read_b64_tr_b16 v[160:161], v4 offset:25600
	ds_read_b64_tr_b16 v[162:163], v4 offset:26112
	s_waitcnt lgkmcnt(11)
	v_mfma_f32_32x32x16_bf16 v[80:95], v[192:195], v[140:143], v[80:95]
	v_add_f32_e32 v2, v122, v2
	v_add_f32_e32 v2, v123, v2
	v_add_f32_e32 v2, v124, v2
	v_add_f32_e32 v2, v125, v2
	v_cvt_pk_bf16_f32 v152, v120, v121
	v_cvt_pk_bf16_f32 v153, v122, v123
	ds_read_b64_tr_b16 v[116:117], v4 offset:29696
	ds_read_b64_tr_b16 v[118:119], v4 offset:30208
	s_waitcnt lgkmcnt(12)
	v_mfma_f32_32x32x16_bf16 v[64:79], v[184:187], v[140:143], v[64:79]
	v_add_f32_e32 v2, v126, v2
	v_add_f32_e32 v2, v127, v2
	v_add_f32_e32 v2, v96, v2
	v_add_f32_e32 v2, v97, v2
	v_cvt_pk_bf16_f32 v154, v124, v125
	v_cvt_pk_bf16_f32 v155, v126, v127
	ds_read_b64_tr_b16 v[112:113], v4 offset:26624
	ds_read_b64_tr_b16 v[114:115], v4 offset:27136
	s_waitcnt lgkmcnt(13)
	v_mfma_f32_32x32x16_bf16 v[80:95], v[188:191], v[132:135], v[80:95]
	v_add_f32_e32 v2, v98, v2
	v_add_f32_e32 v2, v99, v2
	v_add_f32_e32 v2, v100, v2
	v_add_f32_e32 v2, v101, v2
	v_cvt_pk_bf16_f32 v144, v96, v97
	v_cvt_pk_bf16_f32 v145, v98, v99
	ds_read_b64_tr_b16 v[10:11], v4 offset:30720
	ds_read_b64_tr_b16 v[12:13], v4 offset:31232
	s_waitcnt lgkmcnt(14)
	v_mfma_f32_32x32x16_bf16 v[64:79], v[176:179], v[132:135], v[64:79]
	v_add_f32_e32 v2, v102, v2
	v_add_f32_e32 v2, v103, v2
	v_add_f32_e32 v2, v104, v2
	v_add_f32_e32 v2, v105, v2
	v_cvt_pk_bf16_f32 v146, v100, v101
	v_cvt_pk_bf16_f32 v147, v102, v103
	ds_read_b64_tr_b16 v[6:7], v4 offset:27648
	ds_read_b64_tr_b16 v[8:9], v4 offset:28160
	s_waitcnt lgkmcnt(14)
	v_mfma_f32_32x32x16_bf16 v[80:95], v[180:183], v[128:131], v[80:95]
	v_add_f32_e32 v2, v106, v2
	v_add_f32_e32 v2, v107, v2
	v_add_f32_e32 v2, v108, v2
	v_add_f32_e32 v15, v109, v2
	v_cvt_pk_bf16_f32 v136, v104, v105
	v_cvt_pk_bf16_f32 v137, v106, v107
	ds_read_b64_tr_b16 v[2:3], v4 offset:31744
	ds_read_b64_tr_b16 v[4:5], v4 offset:32256
	v_mfma_f32_32x32x16_bf16 v[64:79], v[172:175], v[128:131], v[64:79]
	v_add_f32_e32 v15, v110, v15
	v_add_f32_e32 v15, v111, v15
	v_cvt_pk_bf16_f32 v138, v108, v109
	v_cvt_pk_bf16_f32 v139, v110, v111
	v_max3_f32 v96, v80, v81, v82
	v_max3_f32 v97, v83, v84, v85
	v_max3_f32 v96, v96, v86, v87
	v_max3_f32 v97, v97, v88, v89
	v_max3_f32 v96, v96, v90, v91
	v_max3_f32 v97, v97, v92, v93
	v_max3_f32 v96, v96, v94, v95
	v_add_f32_e32 v223, v14, v15
	s_nop 0
	v_max3_f32 v97, v97, v64, v65
	v_max3_f32 v96, v96, v66, v67
	v_max3_f32 v97, v97, v68, v69
	v_max3_f32 v96, v96, v70, v71
	v_max3_f32 v97, v97, v72, v73
	v_max3_f32 v96, v96, v74, v75
	v_max3_f32 v97, v97, v76, v77
	v_max3_f32 v96, v96, v78, v79
	v_max_f32_e32 v14, v96, v97
	v_mov_b32_e32 v15, v14
	s_nop 1
	v_permlane32_swap_b32_e32 v14, v15
	v_max_f32_e32 v14, v14, v15
	v_cmp_lt_f32_e32 vcc, s53, v14
	s_cmp_lg_u64 vcc, 0
	s_cselect_b64 s[8:9], -1, 0
	s_cbranch_vccnz .LBB0_1558
